# ret scan LDS images: row pad 16->32 bytes (second measurement)
# speedup vs baseline: 1.0035x; 1.0035x over previous
;     __host__ __device__ bool next(int i, Unit& u) const { return StaticOrder::next(i >> 1, u); }
;     __device__ __forceinline__ bool next(int i, Unit& u) const { const int s = i * G + c; if (s >= 128) return false; const int t = s >> 2; u.pm = pm0 + (t & 3); u.pn = t >> 2; u.k0 = (s & 3) * ksub; return true; }
;     __host__ __device__ bool next(int i, Unit& u) const {
;         const long L = (long)i * G + c; if (!(PG8_ROUND_MAJOR && G % NXCD == 0) && L >= nwg) return false; if ((long)i * G >= nwg) return false;
;         int wgid = (int)L;
;         if (PG8_ROUND_MAJOR && G % NXCD == 0) { const int per = G / NXCD; wgid = ((i * NXCD) + (c % NXCD)) * per + (c / NXCD); if (wgid >= nwg) return false; }
;         else { const int q = nwg / NXCD, r = nwg % NXCD, xcd = wgid % NXCD, off = wgid / NXCD; wgid = (xcd < r ? xcd * (q + 1) : r * (q + 1) + (xcd - r) * q) + off; }
;         const int nig = wgm * nN, gid = wgid / nig, fm = gid * wgm, gsz = (nM - fm) < wgm ? (nM - fm) : wgm;
;         u.pm = fm + ((wgid % nig) % gsz); u.pn = (wgid % nig) / gsz; u.k0 = 0; return true;
; __global__ void __launch_bounds__(NWAVES * 64, 2) fwd_kernel(Args args_in) {
;     ...
;         const bool last = (layer == DEPTH - 1), hg = (layer & 1) != 0;
;         const int j = layer >> 1;
;         const int Mr = last ? ML : M;
;     ...
;         const int tc_slot = ((int)blockIdx.x & 7) * 32 + ((int)blockIdx.x >> 3);
;         const int tc_rem1 = (hg ? (M / 256) * 40 : (M / 256) * 32) % 256, tc_idle1 = 256 - tc_rem1;
;         const float* modl = MOD + (size_t)layer * 5 * MOD_LD;
;         unsigned char* wb = ws + WS_W + (size_t)layer * W_LAYER;
.LBB0_201:
	s_cmpk_eq_i32 s3, 0x100
	s_cselect_b64 s[0:1], -1, 0
	v_writelane_b32 v254, s0, 20
	s_cmpk_lg_i32 s3, 0x100
	s_mov_b32 s85, 0
	v_writelane_b32 v254, s1, 21
	s_cselect_b64 s[0:1], -1, 0
	v_writelane_b32 v254, s0, 22
	s_ashr_i32 s97, s2, 31
	s_lshl_b32 s42, s3, 3
	v_writelane_b32 v254, s1, 23
	s_lshl_b32 s0, s2, 5
	s_and_b32 s0, s0, 0xe0
	s_ashr_i32 s1, s2, 3
	s_add_i32 s8, s0, s1
	s_lshr_b32 s0, s97, 29
	s_add_i32 s0, s2, s0
	s_ashr_i32 s10, s0, 3
	s_and_b32 s0, s0, -8
	s_sub_i32 s11, s2, s0
	s_ashr_i32 s0, s3, 3
	v_readlane_b32 s1, v254, 4
	v_writelane_b32 v254, s0, 24
	s_mul_i32 s0, s0, s11
	s_lshl_b32 s91, s1, 3
	s_add_i32 s14, s0, s10
	s_ashr_i32 s65, s3, 31
	s_cmpk_lt_i32 s1, 0x100
	s_cselect_b64 s[0:1], -1, 0
	v_writelane_b32 v254, s0, 25
	s_cmpk_lt_i32 s2, 0x200
	s_mov_b32 s52, 0xf7800000
	v_writelane_b32 v254, s1, 26
	s_cselect_b64 s[0:1], -1, 0
	s_lshl_b32 s6, s11, 6
	s_cmpk_lt_i32 s14, 0x200
	s_cselect_b64 s[4:5], -1, 0
	s_cmpk_lt_i32 s2, 0x80
	s_cselect_b64 s[12:13], -1, 0
	v_writelane_b32 v254, s12, 27
	s_bfe_u32 s7, s2, 0x20002
	s_or_b32 s9, s7, 64
	v_writelane_b32 v254, s13, 28
	s_lshl_b32 s7, s2, 9
	v_writelane_b32 v254, s9, 29
	s_lshl_b32 s9, s9, 20
	s_and_b32 s7, s7, 0x600
	v_writelane_b32 v254, s9, 30
	s_ashr_i32 s16, s2, 4
	v_writelane_b32 v254, s7, 31
	s_lshl_b32 s7, s7, 1
	v_writelane_b32 v254, s7, 32
	s_mov_b32 s12, s16
	s_ashr_i32 s17, s16, 31
	v_writelane_b32 v254, s12, 33
	v_cndmask_b32_e64 v1, 0, 1, s[0:1]
	v_cndmask_b32_e64 v0, 0, 1, s[4:5]
	v_writelane_b32 v254, s13, 34
	s_lshl_b64 s[12:13], s[16:17], 20
	v_writelane_b32 v254, s12, 35
	s_cmpk_gt_i32 s2, 0x7f
	v_cndmask_b32_e64 v0, v1, v0, s[38:39]
	v_writelane_b32 v254, s13, 36
	s_cselect_b64 s[12:13], -1, 0
	s_lshl_b32 s7, s2, 3
	v_writelane_b32 v254, s12, 37
	s_add_i32 s9, s7, 0xfffffc00
	s_cmpk_gt_i32 s8, 0xaf
	v_writelane_b32 v254, s13, 38
	v_writelane_b32 v254, s9, 39
	s_cselect_b64 s[12:13], -1, 0
	v_writelane_b32 v254, s12, 40
	s_addk_i32 s7, 0x2a00
	v_and_b32_e32 v0, 1, v0
	v_writelane_b32 v254, s13, 41
	v_writelane_b32 v254, s8, 42
	s_lshl_b32 s8, s8, 3
	s_addk_i32 s8, 0xa80
	v_writelane_b32 v254, s8, 43
	s_and_b32 s8, s2, 3
	v_writelane_b32 v254, s7, 44
	s_mul_i32 s9, s8, 0x580
	v_writelane_b32 v254, s9, 45
	s_mulk_i32 s8, 0xb00
	s_cmp_lt_i32 s11, 0
	v_writelane_b32 v254, s8, 46
	s_movk_i32 s8, 0x155
	s_movk_i32 s9, 0x111
	s_mul_i32 s7, s11, 0x41
	s_cselect_b32 s8, s8, 0x154
	s_cselect_b32 s9, s9, 0x110
	s_mul_i32 s8, s11, s8
	s_mul_i32 s9, s11, s9
	s_cselect_b32 s6, s7, s6
	v_writelane_b32 v254, s10, 47
	s_add_i32 s8, s8, s10
	s_add_i32 s9, s9, s10
	s_add_i32 s10, s6, s10
	v_writelane_b32 v254, s11, 48
	s_lshr_b32 s6, s11, 31
	v_writelane_b32 v254, s6, 49
	s_and_b64 s[6:7], s[38:39], exec
	s_cselect_b32 s11, s14, s2
	s_cmpk_lt_i32 s11, 0xaa0
	s_cselect_b64 s[6:7], -1, 0
	v_writelane_b32 v254, s6, 50
	s_waitcnt lgkmcnt(0)
;     __host__ __device__ bool next(int i, Unit& u) const { return StaticOrder::next(i >> 1, u); }
;     __device__ __forceinline__ bool next(int i, Unit& u) const { const int s = i * G + c; if (s >= 128) return false; const int t = s >> 2; u.pm = pm0 + (t & 3); u.pn = t >> 2; u.k0 = (s & 3) * ksub; return true; }
;     __host__ __device__ bool next(int i, Unit& u) const {
;         const long L = (long)i * G + c; if (!(PG8_ROUND_MAJOR && G % NXCD == 0) && L >= nwg) return false; if ((long)i * G >= nwg) return false;
;         int wgid = (int)L;
;         if (PG8_ROUND_MAJOR && G % NXCD == 0) { const int per = G / NXCD; wgid = ((i * NXCD) + (c % NXCD)) * per + (c / NXCD); if (wgid >= nwg) return false; }
;         else { const int q = nwg / NXCD, r = nwg % NXCD, xcd = wgid % NXCD, off = wgid / NXCD; wgid = (xcd < r ? xcd * (q + 1) : r * (q + 1) + (xcd - r) * q) + off; }
;         const int nig = wgm * nN, gid = wgid / nig, fm = gid * wgm, gsz = (nM - fm) < wgm ? (nM - fm) : wgm;
;         u.pm = fm + ((wgid % nig) % gsz); u.pn = (wgid % nig) / gsz; u.k0 = 0; return true;
;     ...
;     constexpr int HD = HG ? 128 : 256, NH = HG ? 16 : 8, NEB = HD / 64, C = 64, NCTX = CTXL / C, NCH = (CTXL + SEQ) / C;
;     constexpr int KS = HD / 32;
;     constexpr int DT = HD / 128;
;     constexpr int QS = HD * 2 + (MX_SWZ ? 0 : 16);
;     constexpr int IMG = 64 * QS;
;     constexpr int PS = MX_PS;
;     constexpr int NI = HG ? 4 : 2;
;     constexpr int O_VT = NI * IMG, O_P = O_VT + 64 * PS, O_ST = O_P + 64 * PS, O_TOT = O_ST + IMG, O_END = O_TOT + 4 * 128 * 4 + 128 * 4;
	s_mov_b32 s69, 0x3c000
	v_mov_b32_e32 v252, 0x358637bd
	v_writelane_b32 v254, s7, 51
	s_and_b64 s[6:7], s[38:39], exec
	s_cselect_b32 s6, s14, s8
	s_mul_hi_i32 s7, s6, 0x66666667
	s_lshr_b32 s8, s7, 31
	s_ashr_i32 s7, s7, 6
	s_add_i32 s7, s7, s8
	s_lshl_b32 s8, s7, 2
	s_sub_i32 s12, 0x44, s8
	s_mulk_i32 s7, 0xa0
	s_min_i32 s12, s12, 4
	s_sub_i32 s13, s6, s7
	s_cmpk_lt_i32 s11, 0x880
	s_cselect_b64 s[6:7], -1, 0
	v_writelane_b32 v254, s6, 52
	s_mov_b32 s55, 0xf800000
	v_mov_b32_e32 v253, 0x260
	v_writelane_b32 v254, s7, 53
	s_and_b64 s[6:7], s[38:39], exec
	s_cselect_b32 s6, s14, s9
	s_ashr_i32 s7, s6, 31
	s_lshr_b32 s7, s7, 25
	s_add_i32 s7, s6, s7
	s_ashr_i32 s9, s7, 7
	s_lshl_b32 s9, s9, 2
	s_sub_i32 s11, 0x44, s9
	s_and_b32 s7, s7, 0xffffff80
	s_min_i32 s11, s11, 4
	s_sub_i32 s6, s6, s7
	s_and_b64 s[0:1], s[38:39], exec
	s_cselect_b32 s0, s14, s10
	s_abs_i32 s5, s12
	v_cvt_f32_u32_e32 v1, s5
	v_writelane_b32 v254, s14, 54
	s_sub_i32 s14, 0, s5
	s_ashr_i32 s1, s0, 31
	v_rcp_iflag_f32_e32 v1, v1
	s_lshr_b32 s1, s1, 27
	s_add_i32 s1, s0, s1
	s_abs_i32 s10, s13
	v_mul_f32_e32 v1, 0x4f7ffffe, v1
	v_cvt_u32_f32_e32 v1, v1
	s_ashr_i32 s4, s1, 5
	s_lshl_b32 s4, s4, 2
	s_andn2_b32 s1, s1, 31
	v_readfirstlane_b32 s15, v1
	s_mul_i32 s14, s14, s15
	s_mul_hi_u32 s14, s15, s14
	s_add_i32 s15, s15, s14
	s_mul_hi_u32 s14, s10, s15
	s_mul_i32 s15, s14, s5
	s_sub_i32 s7, 64, s4
	s_sub_i32 s0, s0, s1
	s_xor_b32 s1, s13, s12
	s_sub_i32 s10, s10, s15
	s_min_i32 s7, s7, 4
	s_ashr_i32 s1, s1, 31
	s_add_i32 s15, s14, 1
	s_sub_i32 s16, s10, s5
	s_cmp_ge_u32 s10, s5
	s_cselect_b32 s14, s15, s14
	s_cselect_b32 s10, s16, s10
	s_add_i32 s15, s14, 1
	s_cmp_ge_u32 s10, s5
	s_cselect_b32 s5, s15, s14
	s_abs_i32 s10, s11
	v_cvt_f32_u32_e32 v1, s10
	s_xor_b32 s5, s5, s1
	s_sub_i32 s1, s5, s1
	v_writelane_b32 v254, s1, 55
	v_rcp_iflag_f32_e32 v1, v1
	s_mul_i32 s1, s1, s12
	s_sub_i32 s1, s13, s1
	s_add_i32 s1, s8, s1
	v_mul_f32_e32 v1, 0x4f7ffffe, v1
	v_cvt_u32_f32_e32 v1, v1
	s_sub_i32 s8, 0, s10
	s_abs_i32 s5, s6
	v_writelane_b32 v254, s1, 56
	v_readfirstlane_b32 s12, v1
	s_mul_i32 s8, s8, s12
	s_mul_hi_u32 s8, s12, s8
	s_add_i32 s12, s12, s8
	s_mul_hi_u32 s8, s5, s12
	s_mul_i32 s12, s8, s10
	s_xor_b32 s1, s6, s11
	s_sub_i32 s5, s5, s12
	s_ashr_i32 s1, s1, 31
	s_add_i32 s12, s8, 1
	s_sub_i32 s13, s5, s10
	s_cmp_ge_u32 s5, s10
	s_cselect_b32 s8, s12, s8
	s_cselect_b32 s5, s13, s5
	s_add_i32 s12, s8, 1
	s_cmp_ge_u32 s5, s10
	s_cselect_b32 s5, s12, s8
	s_abs_i32 s8, s7
	v_cvt_f32_u32_e32 v1, s8
	s_xor_b32 s5, s5, s1
	s_sub_i32 s1, s5, s1
	v_writelane_b32 v254, s1, 57
	v_rcp_iflag_f32_e32 v1, v1
	s_mul_i32 s1, s1, s11
	s_sub_i32 s1, s6, s1
	s_add_i32 s1, s9, s1
	v_mul_f32_e32 v1, 0x4f7ffffe, v1
	v_cvt_u32_f32_e32 v1, v1
	s_sub_i32 s6, 0, s8
	s_abs_i32 s5, s0
	v_writelane_b32 v254, s1, 58
	v_readfirstlane_b32 s9, v1
	s_mul_i32 s6, s6, s9
	s_mul_hi_u32 s6, s9, s6
	s_add_i32 s9, s9, s6
	s_mul_hi_u32 s6, s5, s9
	s_mul_i32 s9, s6, s8
	s_xor_b32 s1, s0, s7
	s_sub_i32 s5, s5, s9
	s_ashr_i32 s1, s1, 31
	s_add_i32 s9, s6, 1
	s_sub_i32 s10, s5, s8
	s_cmp_ge_u32 s5, s8
	s_cselect_b32 s6, s9, s6
	s_cselect_b32 s5, s10, s5
	s_add_i32 s9, s6, 1
	s_cmp_ge_u32 s5, s8
	s_cselect_b32 s5, s9, s6
	s_xor_b32 s5, s5, s1
	s_sub_i32 s6, s5, s1
	s_mul_i32 s1, s6, s7
	s_sub_i32 s0, s0, s1
	s_add_i32 s4, s4, s0
	s_ashr_i32 s0, s91, 31
	v_writelane_b32 v254, s0, 59
	s_add_i32 s0, 0, 0x20160
	v_writelane_b32 v254, s0, 60
	s_add_i32 s0, 0, 0x20164
	v_writelane_b32 v254, s0, 61
	s_add_i32 s0, 0, 0x11400
	v_writelane_b32 v254, s0, 62
	s_add_i32 s0, 0, 0x13800
	v_writelane_b32 v254, s0, 63
	s_add_i32 s0, 0, 0x16000
	v_writelane_b32 v255, s0, 0
	s_add_i32 s0, 0, 0x11000
	v_writelane_b32 v255, s0, 1
	v_cmp_eq_u32_e64 s[0:1], 1, v0
	s_ashr_i32 s5, s4, 31
	s_ashr_i32 s7, s6, 31
	v_writelane_b32 v255, s0, 2
	s_ashr_i32 s43, s42, 31
	v_mov_b32_e32 v1, 0
	v_writelane_b32 v255, s1, 3
	s_mov_b32 s0, s4
	v_writelane_b32 v255, s0, 4
	s_movk_i32 s94, 0x7ff
	v_mov_b32_e32 v182, 0x42a00000
	v_writelane_b32 v255, s1, 5
	s_lshl_b64 s[0:1], s[4:5], 20
	v_writelane_b32 v255, s0, 6
	v_mov_b32_e32 v183, 0x7f800000
	s_mov_b32 s95, 0xc2a00000
	v_writelane_b32 v255, s1, 7
	s_mov_b32 s0, s6
	v_writelane_b32 v255, s0, 8
	s_mov_b32 s50, 0x20000
	s_mov_b32 s90, 0x30000
	v_writelane_b32 v255, s1, 9
	s_lshl_b64 s[0:1], s[6:7], 20
	v_writelane_b32 v255, s0, 10
	s_mov_b32 s83, 0x80000
	s_mov_b32 s64, 0x50000
	v_writelane_b32 v255, s1, 11
	s_mov_b32 s67, 0xd5800000
	s_lshl_b64 s[74:75], s[42:43], 12
	s_mov_b32 s53, -1
	s_mov_b32 s96, 0xbfb8aa3b
	s_mov_b32 s68, 0x3f317218
	s_mov_b32 s56, 0x3fb8aa3b
	s_mov_b32 s54, 0x3d800000
	s_mov_b64 s[72:73], s[70:71]
	s_mov_b32 s76, s85
	v_writelane_b32 v255, s91, 12
	s_branch .LBB0_205

; #define LAS __attribute__((address_space(3)))
;     ...
;     const int lane = F.lane, w = F.wave, tid = F.tid, g = lane >> 4, i = lane & 15;
;     const int rg = w >> 1, cg = w & 1, nq0 = 16 * rg;
;     LAS unsigned char* const L = F.lds;
;     const bf16* act = (const bf16*)(a.ws + WS_ACT);
;     for (int task = F.vcu; task < BATCH * NH * 2 * NEB; task += F.G) {
;         const int eb = task % NEB, dir = (task / NEB) & 1, h = (task / (2 * NEB)) % NH, b = task / (2 * NEB * NH);
;         bf16* O = (bf16*)(a.ws + (dir ? WS_OB : WS_OF));
;         const bf16* src0 = act;
;         const bf16* src1 = act + (size_t)(HG ? (2 + 2 * dir) : 1) * ACT_STRIDE;
;         const bf16* src2 = act + (size_t)(1 + 2 * dir) * ACT_STRIDE;
;         const bf16* srcv = act + (size_t)(HG ? 5 : 2) * ACT_STRIDE;
;         float lg2 = 0.f;
;         if (!HG) { const float x = a.in[10][(j_layer * 2 + dir) * 8 + h]; lg2 = -log1pf(expf(-x)) * 1.4426950408889634f; }
;         const float r1 = HG ? 1.f : exp2f((float)(nq0 + i - 63) * lg2), r2 = HG ? 1.f : exp2f((float)(nq0 + i + 1) * lg2), cdec = HG ? 1.f : exp2f(64.f * lg2);
;         const int vrow = tid & 63, vcc = tid >> 6;
;         const int vs = dir ? 63 - vrow : vrow;
;         const float kdec = HG ? 1.f : exp2f((float)(63 - vs) * lg2);
;         f32x4 accS[DT][4];
; #pragma unroll
;         for (int td = 0; td < DT; ++td)
; #pragma unroll
;             for (int te = 0; te < 4; ++te) accS[td][te] = ZERO4;
;         constexpr int NPQ = HG ? 2 : 4;
;         constexpr int PF = HG ? MX_PF_HG : MX_PF_RET;
;         static_assert(NCH % PF == 0, "prefetch depth must divide the chunk count");
;         v4u rq[PF][HG ? 3 : 2][NPQ]; v4u rv[PF];
;     ...
;         __syncthreads();
;         for (int u = tid; u < IMG / 16; u += NWAVES * 64) { const unsigned zu_ = __builtin_bit_cast(unsigned, zf_); *(LAS v4u*)(L + O_ST + u * 16) = (v4u){zu_, zu_, zu_, zu_}; }
.LBB0_795:
	s_andn2_b64 vcc, exec, s[6:7]
	s_cbranch_vccnz .LBB0_855
	s_getreg_b32 s6, hwreg(HW_REG_HW_ID, 0, 6)
	s_lshl_b32 s6, s6, 2
	s_add_i32 s6, s6, 0
	s_add_i32 s6, s6, 0x20540
	v_mov_b32_e32 v0, s6
	ds_read_b32 v0, v0
	v_mbcnt_lo_u32_b32 v3, -1, 0
	v_mbcnt_hi_u32_b32 v3, -1, v3
	v_mov_b32_e32 v2, v1
	s_waitcnt lgkmcnt(0)
	v_readfirstlane_b32 s6, v0
	s_nop 1
	v_lshl_add_u32 v0, s6, 6, v3
	v_readlane_b32 s6, v254, 25
	v_readlane_b32 s7, v254, 26
	s_andn2_b64 vcc, exec, s[6:7]
	v_readfirstlane_b32 s24, v0
	s_cbranch_vccnz .LBB0_809
	s_waitcnt vmcnt(0)
	v_mov_b64_e32 v[4:5], s[0:1]
	s_waitcnt vmcnt(0)
	flat_load_dwordx2 v[6:7], v[4:5] offset:152
	s_ashr_i32 s8, s24, 6
	v_ashrrev_i32_e32 v16, 31, v0
	v_add_u32_e32 v17, 0x200, v0
	s_lshl_b32 s9, s8, 3
	s_lshl_b32 s8, s8, 5
	v_lshrrev_b32_e32 v16, 27, v16
	v_ashrrev_i32_e32 v19, 31, v17
	s_mov_b64 s[26:27], 0xd000000
	v_and_b32_e32 v11, 15, v0
	v_readlane_b32 s29, v255, 0
	s_and_b32 s25, s8, 32
	v_add_u32_e32 v16, v0, v16
	v_lshrrev_b32_e32 v19, 27, v19
	v_mov_b32_e32 v15, s29
	s_movk_i32 s12, 0x220
	v_or_b32_e32 v23, s25, v11
	v_ashrrev_i32_e32 v149, 5, v16
	v_and_b32_e32 v16, 0xffffffe0, v16
	v_add_u32_e32 v19, v17, v19
	v_mad_u32_u24 v155, v23, s12, v15
	v_sub_u32_e32 v15, v0, v16
	v_and_b32_e32 v16, 0xffffffe0, v19
	v_bfe_u32 v9, v0, 4, 2
	v_bfe_u32 v12, v0, 2, 2
	v_lshrrev_b32_e32 v13, 1, v0
	v_lshlrev_b32_e32 v10, 2, v9
	v_bfi_b32 v119, -16, s9, v0
	s_movk_i32 s28, 0xa0
	v_lshlrev_b32_e32 v14, 3, v0
	v_lshlrev_b32_e32 v18, 3, v9
	v_and_or_b32 v12, v13, 24, v12
	v_subrev_u32_e32 v20, 63, v119
	v_add_u32_e32 v21, 1, v119
	v_mul_lo_u32 v22, v119, s12
	v_or_b32_e32 v24, s25, v10
	v_mul_lo_u32 v25, v119, s28
	v_readlane_b32 s13, v254, 63
	v_ashrrev_i32_e32 v8, 3, v0
	v_and_b32_e32 v13, 8, v14
	v_and_b32_e32 v148, 8, v18
	v_mul_u32_u24_e32 v12, 0x220, v12
	v_cvt_f32_i32_e32 v150, v20
	v_cvt_f32_i32_e32 v151, v21
	v_add_u32_e32 v152, 0, v22
	v_or_b32_e32 v20, 2, v24
	v_add_u32_e32 v154, s13, v25
	v_lshlrev_b32_e32 v22, 1, v24
	v_or_b32_e32 v25, 16, v24
	v_readlane_b32 s6, v255, 14
	s_andn2_b32 s24, s24, 63
	v_and_b32_e32 v8, -8, v8
	v_add3_u32 v12, 0, v12, v13
	v_add_u32_e32 v13, s29, v148
	v_mad_u32_u24 v153, v23, s12, 0
	v_ashrrev_i32_e32 v156, 5, v19
	v_cmp_gt_i32_e64 s[12:13], v20, v119
	v_and_b32_e32 v19, 0x50, v22
	v_lshlrev_b32_e32 v20, 1, v25
	v_readlane_b32 s7, v255, 15
	s_lshl_b32 s33, s6, 4
	s_movk_i32 s6, 0x880
	v_and_b32_e32 v117, 48, v0
	v_ashrrev_i32_e32 v9, 31, v8
	v_cmp_gt_i32_e64 s[8:9], v24, v119
	v_cmp_lt_i32_e64 s[10:11], v24, v119
	v_or_b32_e32 v21, 3, v24
	v_or_b32_e32 v26, 17, v24
	v_or_b32_e32 v27, 18, v24
	v_or_b32_e32 v24, 19, v24
	v_lshlrev_b32_e32 v157, 3, v15
	v_add_u32_e32 v158, v154, v19
	v_and_b32_e32 v19, 0x70, v20
	v_lshlrev_b32_e32 v112, 4, v15
	v_mul_lo_u32 v165, v8, s28
	v_and_or_b32 v14, v14, 16, s24
	v_and_b32_e32 v113, 63, v0
	v_mov_b32_e32 v3, v2
	v_mov_b32_e32 v4, v2
	v_mov_b32_e32 v5, v2
	s_waitcnt vmcnt(0) lgkmcnt(0)
	v_lshl_add_u64 v[106:107], v[6:7], 0, s[26:27]
	s_mov_b64 s[26:27], 0x11400000
	v_lshl_add_u64 v[108:109], v[6:7], 0, s[26:27]
	s_mov_b64 s[26:27], 0x15800000
	v_lshl_add_u64 v[110:111], v[6:7], 0, s[26:27]
	v_add_u32_e32 v7, 0x400, v0
	v_sub_u32_e32 v6, v17, v16
	v_ashrrev_i32_e32 v16, 31, v7
	v_lshrrev_b32_e32 v16, 27, v16
	v_add_u32_e32 v16, v7, v16
	v_ashrrev_i32_e32 v161, 5, v16
	v_and_b32_e32 v16, 0xffffffe0, v16
	v_sub_u32_e32 v7, v7, v16
	v_add_u32_e32 v16, 0x600, v0
	v_ashrrev_i32_e32 v17, 31, v16
	v_lshrrev_b32_e32 v17, 27, v17
	v_add_u32_e32 v17, v16, v17
	v_readlane_b32 s26, v255, 1
	v_lshlrev_b32_e32 v160, 3, v6
	v_ashrrev_i32_e32 v163, 5, v17
	v_and_b32_e32 v17, 0xffffffe0, v17
	v_lshlrev_b32_e32 v114, 4, v6
	v_mov_b32_e32 v6, s26
	v_sub_u32_e32 v16, v16, v17
	v_mad_u32_u24 v167, v11, s28, v6
	v_mad_u32_u24 v168, v23, s28, v6
	v_and_b32_e32 v6, 16, v18
	v_lshlrev_b32_e32 v162, 3, v7
	v_lshlrev_b32_e32 v164, 3, v16
	v_lshlrev_b32_e32 v116, 4, v7
	v_lshlrev_b32_e32 v118, 4, v16
	v_add_u32_e32 v7, 0xa00, v167
	v_add_u32_e32 v15, 0x1400, v167
	v_add_u32_e32 v16, 0x1e00, v167
	v_add3_u32 v6, v13, v6, s24
	v_mul_u32_u24_e32 v11, 0x220, v11
	v_bitop3_b32 v115, v0, 63, v0 bitop3:0xc
	v_cmp_gt_i32_e64 s[6:7], s6, v0
	v_cmp_gt_i32_e64 s[14:15], v21, v119
	v_cmp_gt_i32_e64 s[16:17], v25, v119
	v_cmp_gt_i32_e64 s[18:19], v26, v119
	v_cmp_gt_i32_e64 s[20:21], v27, v119
	v_cmp_gt_i32_e64 s[22:23], v24, v119
	v_add_u32_e32 v159, v154, v19
	v_add_u32_e32 v166, s26, v165
	v_add_u32_e32 v169, 0xfffffe00, v0
	v_lshl_add_u32 v170, v0, 4, s29
	v_lshlrev_b64 v[120:121], 1, v[8:9]
	s_lshl_b32 s84, s25, 1
	v_lshlrev_b32_e32 v0, 1, v10
	v_add_u32_e32 v171, v7, v117
	v_add_u32_e32 v172, v15, v117
	v_add_u32_e32 v173, v16, v117
	v_add_u32_e32 v174, v12, v14
	v_add_u32_e32 v175, v6, v11
	v_readlane_b32 s44, v254, 4
	s_branch .LBB0_799
;     ...
;             MX_STAGE(u);
;             if (MXP_STG > 1) { asm volatile("" ::: "memory"); MX_STAGE(u); }
;             if (HG) {
;                 MX_BAR();
;                 const int d = tid & 127, qr = tid >> 7;
;                 float cl[16], qv[16], kv[16]; float run = 0.f;
; #pragma unroll
;                 for (int ii = 0; ii < 16; ++ii) { const int s = 16 * qr + ii;
;                     const int eo = s * QS + 16 * ((d >> 3) ^ sw16(s)) + (d & 7) * 2;
;                     run += bflo((unsigned)*(const LAS unsigned short*)(L + 2 * IMG + eo)); cl[ii] = run;
;                     qv[ii] = bflo((unsigned)*(const LAS unsigned short*)(L + eo)); kv[ii] = bflo((unsigned)*(const LAS unsigned short*)(L + IMG + eo)); }
;                 LAS float* tot = (LAS float*)(L + O_TOT);
;                 tot[qr * 128 + d] = run;
;                 MX_BAR();
;                 const float t0 = tot[d], t1 = tot[128 + d], t2 = tot[256 + d], t3 = tot[384 + d];
;                 const float off = (qr == 0) ? 0.f : (qr == 1) ? t0 : (qr == 2) ? (t0 + t1) : (t0 + t1 + t2);
;                 const float cref = t0 + t1, cend = (t0 + t1) + (t2 + t3);
;                 if (qr == 0) tot[512 + d] = cend;
; #pragma unroll
;                 for (int ii = 0; ii < 16; ++ii) { const int s = 16 * qr + ii; const float cm = off + cl[ii]; const int eo = s * QS + 16 * ((d >> 3) ^ sw16(s)) + (d & 7) * 2;
;                     const float e1 = __expf(fminf(cm - cref, 80.f)), e2 = __expf(fminf(cref - cm, 80.f)), e3 = __expf(cm), e4 = __expf(cend - cm);
;                     const unsigned w12 = pk2(qv[ii] * e1, kv[ii] * e2), w34 = pk2(qv[ii] * e3, kv[ii] * e4);
;                     *(LAS unsigned short*)(L + eo) = (unsigned short)(w12 & 0xffffu);
;                     *(LAS unsigned short*)(L + IMG + eo) = (unsigned short)(w12 >> 16);
;                     *(LAS unsigned short*)(L + 2 * IMG + eo) = (unsigned short)(w34 & 0xffffu);
;                     *(LAS unsigned short*)(L + 3 * IMG + eo) = (unsigned short)(w34 >> 16); }
;             }
;             MX_BAR();
;             { const int cn = (c + PF < NCH) ? c + PF : NCH - 1; MX_LOAD(cn, u); }
;             if (MXP_SLEEP > 0) __builtin_amdgcn_s_sleep(MXP_SLEEP);
;             const int rlo = MX_ROWLO(c);
;             const bool do_out = ctx_out || c >= NCTX;
;             mx_bf16x8 aq[KS];
;             if (do_out) {
; #pragma unroll
.LBB0_798:
	s_waitcnt vmcnt(0)
	v_lshlrev_b32_e32 v6, 16, v58
	v_and_b32_e32 v7, 0xffff0000, v58
	v_pk_mul_f32 v[6:7], v[136:137], v[6:7]
	ds_write_b128 v191, v[66:69]
	ds_write_b128 v191, v[74:77] offset:34816
	ds_write_b128 v190, v[78:81]
	ds_write_b128 v190, v[86:89] offset:34816
	ds_write_b128 v189, v[90:93]
	ds_write_b128 v189, v[94:97] offset:34816
	ds_write_b128 v188, v[98:101]
	ds_write_b128 v188, v[102:105] offset:34816
	v_cvt_pk_bf16_f32 v6, v6, v7
	ds_write_b16 v177, v6
	ds_write_b16_d16_hi v187, v6 offset:160
	v_lshlrev_b32_e32 v6, 16, v59
	v_and_b32_e32 v7, 0xffff0000, v59
	v_pk_mul_f32 v[6:7], v[136:137], v[6:7]
	v_add_u32_e32 v34, v152, v117
	v_cvt_pk_bf16_f32 v6, v6, v7
	ds_write_b16 v177, v6 offset:320
	ds_write_b16_d16_hi v186, v6 offset:160
	v_lshlrev_b32_e32 v6, 16, v60
	v_and_b32_e32 v7, 0xffff0000, v60
	v_pk_mul_f32 v[6:7], v[136:137], v[6:7]
	s_and_b64 s[24:25], s[24:25], exec
	v_cvt_pk_bf16_f32 v6, v6, v7
	ds_write_b16 v177, v6 offset:640
	ds_write_b16_d16_hi v185, v6 offset:160
	v_lshlrev_b32_e32 v6, 16, v61
	v_and_b32_e32 v7, 0xffff0000, v61
	v_pk_mul_f32 v[6:7], v[136:137], v[6:7]
	v_add_u32_e32 v136, v153, v117
	v_cvt_pk_bf16_f32 v6, v6, v7
	ds_write_b16 v177, v6 offset:960
	ds_write_b16_d16_hi v184, v6 offset:160
	s_waitcnt lgkmcnt(0)
	s_barrier
	ds_read_b128 v[6:9], v34
	ds_read_b128 v[10:13], v34 offset:64
	ds_read_b128 v[14:17], v34 offset:128
	ds_read_b128 v[18:21], v34 offset:192
	ds_read_b128 v[22:25], v34 offset:256
	ds_read_b128 v[26:29], v34 offset:320
	ds_read_b128 v[30:33], v34 offset:384
	ds_read_b128 v[34:37], v34 offset:448
	ds_read_b128 v[58:61], v136 offset:34816
	ds_read_b128 v[66:69], v136 offset:34880
	ds_read_b128 v[74:77], v136 offset:43520
	ds_read_b128 v[78:81], v136 offset:43584
	ds_read_b128 v[86:89], v136 offset:34944
	ds_read_b128 v[90:93], v136 offset:35008
	ds_read_b128 v[94:97], v136 offset:43648
	ds_read_b128 v[98:101], v136 offset:43712
	s_cselect_b32 s24, 0xfc0, 0
	s_or_b32 s24, s24, s30
	s_waitcnt lgkmcnt(7)
	v_mfma_f32_16x16x32_bf16 v[58:61], v[58:61], v[6:9], v[2:5]
	s_waitcnt lgkmcnt(5)
	v_mfma_f32_16x16x32_bf16 v[74:77], v[74:77], v[6:9], v[2:5]
	v_mfma_f32_16x16x32_bf16 v[58:61], v[66:69], v[10:13], v[58:61]
	s_waitcnt lgkmcnt(4)
	v_mfma_f32_16x16x32_bf16 v[66:69], v[78:81], v[10:13], v[74:77]
	s_waitcnt lgkmcnt(3)
	v_mfma_f32_16x16x32_bf16 v[58:61], v[86:89], v[14:17], v[58:61]
	s_waitcnt lgkmcnt(1)
	v_mfma_f32_16x16x32_bf16 v[66:69], v[94:97], v[14:17], v[66:69]
	v_mfma_f32_16x16x32_bf16 v[58:61], v[90:93], v[18:21], v[58:61]
	s_waitcnt lgkmcnt(0)
	v_mfma_f32_16x16x32_bf16 v[66:69], v[98:101], v[18:21], v[66:69]
	ds_read_b128 v[74:77], v136 offset:35072
	ds_read_b128 v[78:81], v136 offset:35136
	ds_read_b128 v[86:89], v136 offset:43776
	ds_read_b128 v[90:93], v136 offset:43840
	ds_read_b128 v[94:97], v136 offset:35200
	ds_read_b128 v[98:101], v136 offset:35264
	ds_read_b128 v[102:105], v136 offset:43904
	ds_read_b128 v[136:139], v136 offset:43968
	s_waitcnt lgkmcnt(7)
	v_mfma_f32_16x16x32_bf16 v[58:61], v[74:77], v[22:25], v[58:61]
	s_waitcnt lgkmcnt(5)
	v_mfma_f32_16x16x32_bf16 v[66:69], v[86:89], v[22:25], v[66:69]
	v_mfma_f32_16x16x32_bf16 v[58:61], v[78:81], v[26:29], v[58:61]
	s_waitcnt lgkmcnt(4)
	v_mfma_f32_16x16x32_bf16 v[66:69], v[90:93], v[26:29], v[66:69]
	s_waitcnt lgkmcnt(3)
	v_mfma_f32_16x16x32_bf16 v[58:61], v[94:97], v[30:33], v[58:61]
	s_waitcnt lgkmcnt(1)
	v_mfma_f32_16x16x32_bf16 v[66:69], v[102:105], v[30:33], v[66:69]
	v_mfma_f32_16x16x32_bf16 v[58:61], v[98:101], v[34:37], v[58:61]
	s_waitcnt lgkmcnt(0)
	v_mfma_f32_16x16x32_bf16 v[66:69], v[136:139], v[34:37], v[66:69]
	s_nop 5
	v_cndmask_b32_e64 v58, v58, 0, s[8:9]
	v_cndmask_b32_e64 v59, 0, v59, s[10:11]
	v_cvt_pk_bf16_f32 v58, v58, v59
	v_cndmask_b32_e64 v59, v60, 0, s[12:13]
	v_cndmask_b32_e64 v60, v61, 0, s[14:15]
	v_cvt_pk_bf16_f32 v59, v59, v60
	v_add_u32_e32 v60, v158, v148
	ds_write_b64 v60, v[58:59]
	v_cndmask_b32_e64 v58, v66, 0, s[16:17]
	v_cndmask_b32_e64 v59, v67, 0, s[18:19]
	v_cvt_pk_bf16_f32 v58, v58, v59
	v_cndmask_b32_e64 v59, v68, 0, s[20:21]
	v_cndmask_b32_e64 v60, v69, 0, s[22:23]
	v_cvt_pk_bf16_f32 v59, v59, v60
	v_add_u32_e32 v60, v159, v148
	ds_write_b64 v60, v[58:59]
	ds_read_b128 v[58:61], v192
	ds_read_b128 v[66:69], v192 offset:64
	ds_read_b128 v[74:77], v171
	ds_read_b128 v[78:81], v171 offset:64
	ds_read_b128 v[86:89], v172
	ds_read_b128 v[90:93], v172 offset:64
	ds_read_b128 v[94:97], v173
	ds_read_b128 v[98:101], v173 offset:64
	ds_read_b64_tr_b16 v[102:103], v174 offset:34816
	ds_read_b64_tr_b16 v[104:105], v174 offset:36992
	ds_read_b64_tr_b16 v[138:139], v174 offset:37024
	ds_read_b64_tr_b16 v[136:137], v174 offset:34848
	ds_read_b64_tr_b16 v[140:141], v174 offset:52224
	ds_read_b64_tr_b16 v[142:143], v174 offset:54400
	ds_read_b64_tr_b16 v[146:147], v174 offset:54432
	ds_read_b64_tr_b16 v[144:145], v174 offset:52256
	v_pk_mul_f32 v[64:65], v[134:135], v[64:65]
	v_pk_mul_f32 v[62:63], v[130:131], v[62:63]
	v_pk_mul_f32 v[44:45], v[134:135], v[44:45]
	v_pk_mul_f32 v[42:43], v[130:131], v[42:43]
	v_pk_mul_f32 v[84:85], v[134:135], v[84:85]
	v_pk_mul_f32 v[82:83], v[130:131], v[82:83]
	v_pk_mul_f32 v[72:73], v[134:135], v[72:73]
	v_pk_mul_f32 v[70:71], v[130:131], v[70:71]
	s_waitcnt lgkmcnt(6)
	v_mfma_f32_16x16x32_bf16 v[62:65], v[102:105], v[86:89], v[62:65]
	v_mul_f32_e64 v56, v134, v56
	v_mul_f32_e64 v57, v135, v57
	v_pk_mul_f32 v[54:55], v[130:131], v[54:55]
	v_pk_mul_f32 v[52:53], v[134:135], v[52:53]
	v_pk_mul_f32 v[50:51], v[130:131], v[50:51]
	v_pk_mul_f32 v[48:49], v[134:135], v[48:49]
	v_pk_mul_f32 v[46:47], v[130:131], v[46:47]
	s_waitcnt lgkmcnt(4)
	v_mfma_f32_16x16x32_bf16 v[42:45], v[136:139], v[86:89], v[42:45]
	v_mul_f32_e64 v40, v134, v40
	v_mul_f32_e64 v41, v135, v41
	v_pk_mul_f32 v[38:39], v[130:131], v[38:39]
	s_waitcnt lgkmcnt(0)
	v_mfma_f32_16x16x32_bf16 v[82:85], v[102:105], v[58:61], v[82:85]
	s_barrier
;     ...
;                     for (int te = 0; te < 4; ++te) accS[td][te] = MX_MFMA(ak[td][0], vt[te][0], accS[td][te] * dec[td]);
; #pragma unroll
;                 for (int td = 0; td < DT; ++td)
; #pragma unroll
;                     for (int te = 0; te < 4; ++te) accS[td][te] = MX_MFMA(ak[td][1], vt[te][1], accS[td][te]);
;             }
;             MX_BAR();
;             if (do_out) {
;                 if (HG) {
; #pragma unroll
;                     for (int ks = 0; ks < KS; ++ks) aq[ks] = frag_row(L + 2 * IMG, QS, nq0, 32 * ks, lane);
;                 }
;                 mx_bf16x8 vo[2][2];
;                 const mx_bf16x8 bp0 = frag_row8(L + O_P, nq0, 0, lane), bp1 = frag_row8(L + O_P, nq0, 32, lane);
; #pragma unroll
;                 for (int te = 0; te < 2; ++te) { vo[te][0] = frag_row8(L + O_VT, 32 * cg + 16 * te, 0, lane); vo[te][1] = frag_row8(L + O_VT, 32 * cg + 16 * te, 32, lane); }
;                 const int grow = rlo + (dir ? 63 - (nq0 + i) : (nq0 + i));
;                 for (int rep2 = 0; rep2 < MXP_S2; ++rep2) {
;                 f32x4 o1a = ZERO4, o1b = o1a, o2a = o1a, o2b = o1a;
; #pragma unroll
;                 for (int kb = 0; kb < KS; kb += 4) {
;                     mx_bf16x8 st[2][4];
; #pragma unroll
;                     for (int ks = 0; ks < 4; ++ks) { st[0][ks] = frag_row(L + O_ST, QS, 32 * cg, 32 * (kb + ks), lane); st[1][ks] = frag_row(L + O_ST, QS, 32 * cg + 16, 32 * (kb + ks), lane); }
;                     __builtin_amdgcn_sched_barrier(0);
;                     if (kb == 0) { o1a = MX_MFMA(vo[0][0], bp0, o1a); o1b = MX_MFMA(vo[1][0], bp0, o1b); o1a = MX_MFMA(vo[0][1], bp1, o1a); o1b = MX_MFMA(vo[1][1], bp1, o1b); }
; #pragma unroll
;                     for (int ks = 0; ks < 4; ++ks) { o2a = MX_MFMA(st[0][ks], aq[kb + ks], o2a); o2b = MX_MFMA(st[1][ks], aq[kb + ks], o2b); }
;                     __builtin_amdgcn_sched_barrier(0);
;                 }
;                 bf16* op = O + (size_t)grow * D + h * HD + eb * 64 + 32 * cg + 4 * g;
;                 if (!(VAR & 2)) { const f32x4 ya = o1a * r1 + o2a * r2, yb = o1b * r1 + o2b * r2; v2u wa, wb; wa.x = pk2(ya[0], ya[1]); wa.y = pk2(ya[2], ya[3]); wb.x = pk2(yb[0], yb[1]); wb.y = pk2(yb[2], yb[3]);
;                     *(GAS v2u*)(op) = wa; *(GAS v2u*)(op + 16) = wb; }
;                 else { asm volatile("" :: "v"(o1a), "v"(o1b), "v"(o2a), "v"(o2b)); }
	v_mfma_f32_16x16x32_bf16 v[70:73], v[102:105], v[74:77], v[70:73]
	v_mfma_f32_16x16x32_bf16 v[54:57], v[102:105], v[94:97], v[54:57]
	v_mfma_f32_16x16x32_bf16 v[50:53], v[136:139], v[58:61], v[50:53]
	v_mfma_f32_16x16x32_bf16 v[46:49], v[136:139], v[74:77], v[46:49]
	v_add_u32_e32 v74, v154, v117
	v_mfma_f32_16x16x32_bf16 v[38:41], v[136:139], v[94:97], v[38:41]
	v_add_u32_e32 v94, s24, v176
	v_ashrrev_i32_e32 v95, 31, v94
	v_lshlrev_b64 v[94:95], 12, v[94:95]
	s_waitcnt lgkmcnt(2)
	v_mfma_f32_16x16x32_bf16 v[62:65], v[140:143], v[90:93], v[62:65]
	v_add_u32_e32 v176, v155, v117
	s_waitcnt lgkmcnt(0)
	v_mfma_f32_16x16x32_bf16 v[42:45], v[144:147], v[90:93], v[42:45]
	v_add_u32_e32 v90, v168, v117
	v_mfma_f32_16x16x32_bf16 v[58:61], v[140:143], v[66:69], v[82:85]
	v_mfma_f32_16x16x32_bf16 v[70:73], v[140:143], v[78:81], v[70:73]
	v_mfma_f32_16x16x32_bf16 v[54:57], v[140:143], v[98:101], v[54:57]
	v_mfma_f32_16x16x32_bf16 v[50:53], v[144:147], v[66:69], v[50:53]
	ds_read_b128 v[66:69], v74
	ds_read_b128 v[74:77], v74 offset:64
	v_mfma_f32_16x16x32_bf16 v[46:49], v[144:147], v[78:81], v[46:49]
	ds_read_b128 v[78:81], v90
	ds_read_b128 v[82:85], v90 offset:64
	ds_read_b128 v[86:89], v90 offset:2560
	ds_read_b128 v[90:93], v90 offset:2624
	v_mfma_f32_16x16x32_bf16 v[38:41], v[144:147], v[98:101], v[38:41]
	v_lshl_add_u64 v[146:147], v[132:133], 0, v[94:95]
	ds_read_b128 v[94:97], v176
	ds_read_b128 v[98:101], v176 offset:8704
	ds_read_b128 v[102:105], v176 offset:64
	ds_read_b128 v[130:133], v176 offset:8768
	ds_read_b128 v[134:137], v176 offset:128
	ds_read_b128 v[138:141], v176 offset:8832
	ds_read_b128 v[142:145], v176 offset:192
	ds_read_b128 v[184:187], v176 offset:8896
	s_waitcnt lgkmcnt(11)
	v_mfma_f32_16x16x32_bf16 v[78:81], v[78:81], v[66:69], v[2:5]
	s_waitcnt lgkmcnt(9)
	v_mfma_f32_16x16x32_bf16 v[66:69], v[86:89], v[66:69], v[2:5]
	v_mfma_f32_16x16x32_bf16 v[78:81], v[82:85], v[74:77], v[78:81]
	s_waitcnt lgkmcnt(8)
	v_mfma_f32_16x16x32_bf16 v[66:69], v[90:93], v[74:77], v[66:69]
	s_waitcnt lgkmcnt(7)
	v_mfma_f32_16x16x32_bf16 v[74:77], v[94:97], v[6:9], v[2:5]
	s_waitcnt lgkmcnt(6)
	v_mfma_f32_16x16x32_bf16 v[82:85], v[98:101], v[6:9], v[2:5]
	s_waitcnt lgkmcnt(5)
	v_mfma_f32_16x16x32_bf16 v[74:77], v[102:105], v[10:13], v[74:77]
	s_waitcnt lgkmcnt(4)
	v_mfma_f32_16x16x32_bf16 v[82:85], v[130:133], v[10:13], v[82:85]
	s_waitcnt lgkmcnt(3)
	v_mfma_f32_16x16x32_bf16 v[74:77], v[134:137], v[14:17], v[74:77]
	s_waitcnt lgkmcnt(2)
	v_mfma_f32_16x16x32_bf16 v[82:85], v[138:141], v[14:17], v[82:85]
	s_waitcnt lgkmcnt(1)
	v_mfma_f32_16x16x32_bf16 v[74:77], v[142:145], v[18:21], v[74:77]
	s_waitcnt lgkmcnt(0)
	v_mfma_f32_16x16x32_bf16 v[82:85], v[184:187], v[18:21], v[82:85]
	ds_read_b128 v[86:89], v176 offset:256
	ds_read_b128 v[90:93], v176 offset:320
	ds_read_b128 v[94:97], v176 offset:8960
	ds_read_b128 v[98:101], v176 offset:9024
	ds_read_b128 v[102:105], v176 offset:384
	ds_read_b128 v[130:133], v176 offset:448
	ds_read_b128 v[134:137], v176 offset:9088
	ds_read_b128 v[138:141], v176 offset:9152
	s_waitcnt lgkmcnt(7)
	v_mfma_f32_16x16x32_bf16 v[74:77], v[86:89], v[22:25], v[74:77]
	s_waitcnt lgkmcnt(5)
	v_mfma_f32_16x16x32_bf16 v[82:85], v[94:97], v[22:25], v[82:85]
	v_mfma_f32_16x16x32_bf16 v[74:77], v[90:93], v[26:29], v[74:77]
	s_waitcnt lgkmcnt(4)
	v_mfma_f32_16x16x32_bf16 v[82:85], v[98:101], v[26:29], v[82:85]
	s_waitcnt lgkmcnt(3)
	v_mfma_f32_16x16x32_bf16 v[74:77], v[102:105], v[30:33], v[74:77]
	s_waitcnt lgkmcnt(1)
	v_mfma_f32_16x16x32_bf16 v[82:85], v[134:137], v[30:33], v[82:85]
	v_mfma_f32_16x16x32_bf16 v[74:77], v[130:133], v[34:37], v[74:77]
	s_waitcnt lgkmcnt(0)
	v_mfma_f32_16x16x32_bf16 v[82:85], v[138:141], v[34:37], v[82:85]
	s_nop 5
	v_mul_f32_e64 v76, v128, v76
	v_mul_f32_e64 v77, v129, v77
	v_pk_mul_f32 v[74:75], v[124:125], v[74:75]
	v_pk_fma_f32 v[76:77], v[126:127], v[80:81], v[76:77]
	v_pk_fma_f32 v[74:75], v[122:123], v[78:79], v[74:75]
	v_pk_mul_f32 v[78:79], v[128:129], v[84:85]
	v_pk_mul_f32 v[80:81], v[124:125], v[82:83]
	v_pk_fma_f32 v[68:69], v[126:127], v[68:69], v[78:79]
	v_pk_fma_f32 v[66:67], v[122:123], v[66:67], v[80:81]
	v_cvt_pk_bf16_f32 v74, v74, v75
	v_cvt_pk_bf16_f32 v75, v76, v77
	v_cvt_pk_bf16_f32 v66, v66, v67
	v_cvt_pk_bf16_f32 v67, v68, v69
	global_store_dwordx2 v[146:147], v[74:75], off
	global_store_dwordx2 v[146:147], v[66:67], off offset:32
	s_waitcnt lgkmcnt(0)
	s_barrier
	s_add_i32 s44, s44, s3
	v_cvt_pk_bf16_f32 v58, v58, v59
	v_cvt_pk_bf16_f32 v59, v60, v61
	v_cvt_pk_bf16_f32 v60, v70, v71
	v_cvt_pk_bf16_f32 v61, v72, v73
	v_cvt_pk_bf16_f32 v62, v62, v63
	v_cvt_pk_bf16_f32 v63, v64, v65
	v_cvt_pk_bf16_f32 v54, v54, v55
	v_cvt_pk_bf16_f32 v55, v56, v57
	v_cvt_pk_bf16_f32 v50, v50, v51
	v_cvt_pk_bf16_f32 v51, v52, v53
	v_cvt_pk_bf16_f32 v46, v46, v47
	v_cvt_pk_bf16_f32 v47, v48, v49
	v_cvt_pk_bf16_f32 v42, v42, v43
	v_cvt_pk_bf16_f32 v43, v44, v45
	v_cvt_pk_bf16_f32 v38, v38, v39
	v_cvt_pk_bf16_f32 v39, v40, v41
	s_cmpk_gt_i32 s44, 0xff
	ds_write2_b64 v175, v[58:59], v[50:51] offset1:4
	ds_write2_b64 v193, v[60:61], v[46:47] offset0:64 offset1:68
	ds_write2_b64 v194, v[62:63], v[42:43] offset0:128 offset1:132
	ds_write2_b64 v195, v[54:55], v[38:39] offset0:192 offset1:196
	s_cbranch_scc1 .LBB0_809

; #define LAS __attribute__((address_space(3)))
;     ...
;         float lg2 = 0.f;
;         if (!HG) { const float x = a.in[10][(j_layer * 2 + dir) * 8 + h]; lg2 = -log1pf(expf(-x)) * 1.4426950408889634f; }
;         const float r1 = HG ? 1.f : exp2f((float)(nq0 + i - 63) * lg2), r2 = HG ? 1.f : exp2f((float)(nq0 + i + 1) * lg2), cdec = HG ? 1.f : exp2f(64.f * lg2);
;         const int vrow = tid & 63, vcc = tid >> 6;
;         const int vs = dir ? 63 - vrow : vrow;
;         const float kdec = HG ? 1.f : exp2f((float)(63 - vs) * lg2);
;         f32x4 accS[DT][4];
; #pragma unroll
;         for (int td = 0; td < DT; ++td)
; #pragma unroll
;             for (int te = 0; te < 4; ++te) accS[td][te] = ZERO4;
;         constexpr int NPQ = HG ? 2 : 4;
;         constexpr int PF = HG ? MX_PF_HG : MX_PF_RET;
;         static_assert(NCH % PF == 0, "prefetch depth must divide the chunk count");
;         v4u rq[PF][HG ? 3 : 2][NPQ]; v4u rv[PF];
;     ...
;         __syncthreads();
;         for (int u = tid; u < IMG / 16; u += NWAVES * 64) { const unsigned zu_ = __builtin_bit_cast(unsigned, zf_); *(LAS v4u*)(L + O_ST + u * 16) = (v4u){zu_, zu_, zu_, zu_}; }
; #pragma unroll
;         for (int u = 0; u < PF; ++u) MX_LOAD(u, u);
.LBB0_801:
	v_add_u32_e32 v44, 0x200, v44
	s_movk_i32 s34, 0x67f
	v_cmp_lt_i32_e64 s[34:35], s34, v44
	ds_write_b128 v43, v[2:5]
	s_or_b64 s[40:41], s[34:35], s[40:41]
	v_add_u32_e32 v43, 0x2000, v43
	s_andn2_b64 exec, exec, s[40:41]
	s_cbranch_execnz .LBB0_801
.LBB0_802:
	s_or_b64 exec, exec, s[36:37]
	v_mov_b32_e32 v46, 0x42800000
	v_cndmask_b32_e64 v43, 0, v46, s[30:31]
	v_fmac_f32_e32 v43, v40, v150
	v_cndmask_b32_e64 v44, 0, v46, s[28:29]
	v_exp_f32_e32 v43, v43
	v_fmac_f32_e32 v44, v40, v151
	v_exp_f32_e32 v44, v44
	v_not_b32_e32 v47, 63
	v_cndmask_b32_e64 v45, 0, v47, s[30:31]
	v_ldexp_f32 v122, v43, v45
	v_cndmask_b32_e64 v43, 0, v47, s[28:29]
	v_ldexp_f32 v124, v44, v43
	v_cndmask_b32_e32 v44, 0, v46, vcc
	v_cndmask_b32_e64 v43, 0, v46, s[26:27]
	v_fmac_f32_e32 v44, v40, v42
	v_cndmask_b32_e64 v42, 0, v47, s[26:27]
	s_and_b64 s[26:27], s[24:25], exec
	s_mov_b32 s26, 0x2ac00000
	s_cselect_b32 s26, s26, 0x33400000
	s_lshl_b32 s28, s51, 2
	s_sub_i32 s30, s44, s28
	s_lshr_b32 s28, s48, 26
	s_add_i32 s28, s44, s28
	v_fmac_f32_e32 v43, 0x42800000, v40
	s_mov_b32 s27, 0
	s_ashr_i32 s40, s28, 6
	v_exp_f32_e32 v43, v43
	v_lshl_add_u64 v[38:39], v[38:39], 0, s[26:27]
	s_lshl_b32 s26, s40, 8
	v_exp_f32_e32 v40, v44
	s_addk_i32 s26, 0x4000
	s_and_b64 s[28:29], s[24:25], exec
	s_cselect_b32 s28, 0, 0xc0
	v_ldexp_f32 v130, v43, v42
	v_cndmask_b32_e32 v42, 0, v47, vcc
	s_or_b32 s41, s28, s26
	v_ldexp_f32 v136, v40, v42
	v_or_b32_e32 v42, s41, v113
	s_lshl_b32 s28, s49, 8
	v_ashrrev_i32_e32 v43, 31, v42
	v_lshlrev_b64 v[42:43], 12, v[42:43]
	s_ashr_i32 s29, s28, 31
	s_lshl_b32 s30, s30, 6
	v_add_u32_e32 v44, s41, v149
	v_lshl_add_u64 v[42:43], v[110:111], 0, v[42:43]
	s_lshl_b64 s[34:35], s[28:29], 1
	s_ashr_i32 s31, s30, 31
	v_ashrrev_i32_e32 v45, 31, v44
	v_add_u32_e32 v138, s28, v157
	v_lshl_add_u64 v[42:43], v[42:43], 0, s[34:35]
	s_lshl_b64 s[36:37], s[30:31], 1
	v_lshlrev_b64 v[44:45], 11, v[44:45]
	v_ashrrev_i32_e32 v139, 31, v138
	v_lshl_add_u64 v[42:43], v[42:43], 0, s[36:37]
	v_lshl_add_u64 v[44:45], v[44:45], 0, v[138:139]
	v_lshl_add_u64 v[42:43], v[42:43], 0, v[120:121]
	v_lshlrev_b64 v[44:45], 1, v[44:45]
	v_lshl_add_u64 v[46:47], v[106:107], 0, v[44:45]
	global_load_dwordx4 v[58:61], v[42:43], off
	global_load_dwordx4 v[66:69], v[46:47], off
	v_lshl_add_u64 v[42:43], v[108:109], 0, v[44:45]
	v_add_u32_e32 v44, s41, v156
	v_ashrrev_i32_e32 v45, 31, v44
	v_add_u32_e32 v140, s28, v160
	v_lshlrev_b64 v[44:45], 11, v[44:45]
	v_ashrrev_i32_e32 v141, 31, v140
	v_lshl_add_u64 v[44:45], v[44:45], 0, v[140:141]
	v_lshlrev_b64 v[44:45], 1, v[44:45]
	v_lshl_add_u64 v[46:47], v[106:107], 0, v[44:45]
	global_load_dwordx4 v[74:77], v[42:43], off
	global_load_dwordx4 v[78:81], v[46:47], off
	v_lshl_add_u64 v[42:43], v[108:109], 0, v[44:45]
	v_add_u32_e32 v44, s41, v161
	v_ashrrev_i32_e32 v45, 31, v44
	v_add_u32_e32 v142, s28, v162
	v_lshlrev_b64 v[44:45], 11, v[44:45]
	v_ashrrev_i32_e32 v143, 31, v142
	v_lshl_add_u64 v[44:45], v[44:45], 0, v[142:143]
	v_lshlrev_b64 v[44:45], 1, v[44:45]
	v_lshl_add_u64 v[46:47], v[106:107], 0, v[44:45]
	global_load_dwordx4 v[86:89], v[42:43], off
	global_load_dwordx4 v[90:93], v[46:47], off
	v_lshl_add_u64 v[42:43], v[108:109], 0, v[44:45]
	v_add_u32_e32 v44, s41, v163
	v_ashrrev_i32_e32 v45, 31, v44
	v_add_u32_e32 v144, s28, v164
	v_lshlrev_b64 v[44:45], 11, v[44:45]
	v_ashrrev_i32_e32 v145, 31, v144
	v_lshl_add_u64 v[44:45], v[44:45], 0, v[144:145]
	v_lshlrev_b64 v[44:45], 1, v[44:45]
	v_lshl_add_u64 v[46:47], v[106:107], 0, v[44:45]
	global_load_dwordx4 v[94:97], v[42:43], off
	global_load_dwordx4 v[98:101], v[46:47], off
	v_lshl_add_u64 v[42:43], v[108:109], 0, v[44:45]
	global_load_dwordx4 v[102:105], v[42:43], off
	v_lshl_add_u64 v[38:39], v[38:39], 0, s[34:35]
	v_lshl_add_u64 v[38:39], v[38:39], 0, s[36:37]
	v_lshl_add_u64 v[38:39], v[38:39], 0, s[84:85]
	v_lshlrev_b32_e32 v40, 1, v41
	v_lshl_add_u64 v[132:133], v[38:39], 0, v[0:1]
	v_sub_u32_e32 v38, 63, v149
	v_and_b32_e32 v46, 0x70, v40
	v_and_b32_e32 v47, 14, v40
	v_readlane_b32 s28, v255, 1
	v_cndmask_b32_e64 v38, v38, v149, s[24:25]
	s_movk_i32 s31, 0x220
	v_add3_u32 v48, s28, v46, v47
	v_lshl_add_u64 v[40:41], v[110:111], 0, s[34:35]
	v_mad_u64_u32 v[38:39], s[28:29], v38, s31, v[112:113]
	v_lshl_add_u64 v[40:41], v[40:41], 0, s[36:37]
	v_sub_u32_e32 v39, 63, v156
	v_lshl_add_u64 v[146:147], v[40:41], 0, v[120:121]
	v_sub_u32_e32 v40, 63, v119
	v_cndmask_b32_e64 v39, v39, v156, s[24:25]
	v_cndmask_b32_e64 v176, v40, v119, s[24:25]
	v_mad_u64_u32 v[40:41], s[28:29], v39, s31, v[114:115]
	v_sub_u32_e32 v39, 63, v161
	v_cndmask_b32_e64 v39, v39, v161, s[24:25]
	v_mad_u64_u32 v[42:43], s[28:29], v39, s31, v[116:117]
	v_sub_u32_e32 v39, 63, v163
	v_cndmask_b32_e64 v39, v39, v163, s[24:25]
	v_mad_u64_u32 v[44:45], s[28:29], v39, s31, v[118:119]
	v_add_u32_e32 v41, 0x140, v166
	v_add_u32_e32 v43, 0x280, v166
	v_add_u32_e32 v45, 0x3c0, v166
	v_add_u32_e32 v39, v166, v46
	v_add_u32_e32 v41, v41, v46
	v_add_u32_e32 v43, v43, v46
	v_add_u32_e32 v45, v45, v46
	s_lshl_b32 s30, s40, 12
	v_mov_b32_e32 v131, v130
	v_mov_b32_e32 v134, v130
	v_mov_b32_e32 v135, v130
	v_mov_b32_e32 v123, v122
	v_mov_b32_e32 v126, v122
	v_mov_b32_e32 v127, v122
	v_mov_b32_e32 v125, v124
	v_mov_b32_e32 v128, v124
	v_mov_b32_e32 v129, v124
	v_mov_b32_e32 v137, v136
	s_movk_i32 s35, 0x43
	v_add_u32_e32 v191, 0, v38
	v_add_u32_e32 v190, 0, v40
	v_add_u32_e32 v189, 0, v42
	v_add_u32_e32 v188, 0, v44
	v_add_u32_e32 v177, v48, v165
	v_add_u32_e32 v187, v39, v47
	v_add_u32_e32 v186, v41, v47
	v_add_u32_e32 v185, v43, v47
	v_add_u32_e32 v184, v45, v47
	v_mov_b32_e32 v38, v2
	v_mov_b32_e32 v39, v2
	v_mov_b32_e32 v40, v2
	v_mov_b32_e32 v41, v2
	v_mov_b32_e32 v42, v2
	v_mov_b32_e32 v43, v2
	v_mov_b32_e32 v44, v2
	v_mov_b32_e32 v45, v2
	v_mov_b32_e32 v46, v2
	v_mov_b32_e32 v47, v2
	v_mov_b32_e32 v48, v2
	v_mov_b32_e32 v49, v2
	v_mov_b32_e32 v50, v2
	v_mov_b32_e32 v51, v2
	v_mov_b32_e32 v52, v2
	v_mov_b32_e32 v53, v2
	v_mov_b32_e32 v54, v2
	v_mov_b32_e32 v55, v2
	v_mov_b32_e32 v56, v2
	v_mov_b32_e32 v57, v2
	v_mov_b32_e32 v62, v2
	v_mov_b32_e32 v63, v2
	v_mov_b32_e32 v64, v2
	v_mov_b32_e32 v65, v2
	v_mov_b32_e32 v70, v2
	v_mov_b32_e32 v71, v2
	v_mov_b32_e32 v72, v2
	v_mov_b32_e32 v73, v2
	v_mov_b32_e32 v82, v2
	v_mov_b32_e32 v83, v2
	v_mov_b32_e32 v84, v2
	v_mov_b32_e32 v85, v2
;     ...
;             MX_STAGE(u);
;             if (MXP_STG > 1) { asm volatile("" ::: "memory"); MX_STAGE(u); }
;             if (HG) {
;                 MX_BAR();
;                 const int d = tid & 127, qr = tid >> 7;
;                 float cl[16], qv[16], kv[16]; float run = 0.f;
; #pragma unroll
;                 for (int ii = 0; ii < 16; ++ii) { const int s = 16 * qr + ii;
;                     const int eo = s * QS + 16 * ((d >> 3) ^ sw16(s)) + (d & 7) * 2;
;                     run += bflo((unsigned)*(const LAS unsigned short*)(L + 2 * IMG + eo)); cl[ii] = run;
;                     qv[ii] = bflo((unsigned)*(const LAS unsigned short*)(L + eo)); kv[ii] = bflo((unsigned)*(const LAS unsigned short*)(L + IMG + eo)); }
;                 LAS float* tot = (LAS float*)(L + O_TOT);
;                 tot[qr * 128 + d] = run;
;                 MX_BAR();
;                 const float t0 = tot[d], t1 = tot[128 + d], t2 = tot[256 + d], t3 = tot[384 + d];
;                 const float off = (qr == 0) ? 0.f : (qr == 1) ? t0 : (qr == 2) ? (t0 + t1) : (t0 + t1 + t2);
;                 const float cref = t0 + t1, cend = (t0 + t1) + (t2 + t3);
;                 if (qr == 0) tot[512 + d] = cend;
; #pragma unroll
;                 for (int ii = 0; ii < 16; ++ii) { const int s = 16 * qr + ii; const float cm = off + cl[ii]; const int eo = s * QS + 16 * ((d >> 3) ^ sw16(s)) + (d & 7) * 2;
;                     const float e1 = __expf(fminf(cm - cref, 80.f)), e2 = __expf(fminf(cref - cm, 80.f)), e3 = __expf(cm), e4 = __expf(cend - cm);
;                     const unsigned w12 = pk2(qv[ii] * e1, kv[ii] * e2), w34 = pk2(qv[ii] * e3, kv[ii] * e4);
;                     *(LAS unsigned short*)(L + eo) = (unsigned short)(w12 & 0xffffu);
;                     *(LAS unsigned short*)(L + IMG + eo) = (unsigned short)(w12 >> 16);
;                     *(LAS unsigned short*)(L + 2 * IMG + eo) = (unsigned short)(w34 & 0xffffu);
;                     *(LAS unsigned short*)(L + 3 * IMG + eo) = (unsigned short)(w34 >> 16); }
;             }
;             MX_BAR();
;             { const int cn = (c + PF < NCH) ? c + PF : NCH - 1; MX_LOAD(cn, u); }
;             if (MXP_SLEEP > 0) __builtin_amdgcn_s_sleep(MXP_SLEEP);
;             const int rlo = MX_ROWLO(c);
;             const bool do_out = ctx_out || c >= NCTX;
;             mx_bf16x8 aq[KS];
;             if (do_out) {
; #pragma unroll
.LBB0_803:
	s_add_i32 s31, s27, 1
	s_add_i32 s34, s35, -1
	v_sub_co_u32_e64 v178, s[36:37], s27, 3
	s_and_b64 s[28:29], s[24:25], exec
	s_waitcnt vmcnt(7)
	ds_write_b128 v191, v[66:69]
	s_waitcnt vmcnt(6)
	ds_write_b128 v191, v[74:77] offset:34816
	s_waitcnt vmcnt(5)
	ds_write_b128 v190, v[78:81]
	s_waitcnt vmcnt(4)
	ds_write_b128 v190, v[86:89] offset:34816
	s_waitcnt vmcnt(3)
	ds_write_b128 v189, v[90:93]
	s_waitcnt vmcnt(2)
	ds_write_b128 v189, v[94:97] offset:34816
	s_waitcnt vmcnt(1)
	ds_write_b128 v188, v[98:101]
	s_waitcnt vmcnt(0)
	ds_write_b128 v188, v[102:105] offset:34816
	v_lshlrev_b32_e32 v66, 16, v58
	v_and_b32_e32 v67, 0xffff0000, v58
	v_readfirstlane_b32 s28, v178
	v_pk_mul_f32 v[66:67], v[136:137], v[66:67]
	s_cselect_b32 s28, s28, s34
	v_cvt_pk_bf16_f32 v58, v66, v67
	s_lshl_b32 s40, s28, 6
	s_add_i32 s41, s35, 0xffffffbf
	ds_write_b16 v177, v58
	ds_write_b16_d16_hi v187, v58 offset:160
	v_lshlrev_b32_e32 v58, 16, v59
	v_and_b32_e32 v59, 0xffff0000, v59
	s_and_b64 s[28:29], s[24:25], exec
	v_pk_mul_f32 v[58:59], v[136:137], v[58:59]
	s_cselect_b32 s28, s31, s41
	v_cvt_pk_bf16_f32 v58, v58, v59
	s_lshl_b32 s28, s28, 6
	ds_write_b16 v177, v58 offset:320
	ds_write_b16_d16_hi v186, v58 offset:160
	v_lshlrev_b32_e32 v58, 16, v60
	v_and_b32_e32 v59, 0xffff0000, v60
	s_add_i32 s41, s28, s26
	v_pk_mul_f32 v[58:59], v[136:137], v[58:59]
	s_cmp_gt_u32 s27, 3
	v_cvt_pk_bf16_f32 v58, v58, v59
	s_cselect_b64 s[28:29], -1, 0
	ds_write_b16 v177, v58 offset:640
	ds_write_b16_d16_hi v185, v58 offset:160
	v_lshlrev_b32_e32 v58, 16, v61
	v_and_b32_e32 v59, 0xffff0000, v61
	s_add_i32 s40, s40, s30
	v_pk_mul_f32 v[58:59], v[136:137], v[58:59]
	s_and_b64 s[36:37], s[36:37], exec
	v_cvt_pk_bf16_f32 v58, v58, v59
	s_cselect_b32 s36, s41, s40
	ds_write_b16 v177, v58 offset:960
	ds_write_b16_d16_hi v184, v58 offset:160
	v_add_u32_e32 v58, s36, v149
	v_ashrrev_i32_e32 v59, 31, v58
	v_lshlrev_b64 v[58:59], 11, v[58:59]
	v_lshl_add_u64 v[58:59], v[58:59], 0, v[138:139]
	v_lshlrev_b64 v[58:59], 1, v[58:59]
	s_waitcnt lgkmcnt(0)
	s_barrier
	v_lshl_add_u64 v[60:61], v[106:107], 0, v[58:59]
	v_lshl_add_u64 v[58:59], v[108:109], 0, v[58:59]
	global_load_dwordx4 v[66:69], v[60:61], off
	global_load_dwordx4 v[74:77], v[58:59], off
	v_add_u32_e32 v58, s36, v156
	v_ashrrev_i32_e32 v59, 31, v58
	v_lshlrev_b64 v[58:59], 11, v[58:59]
	v_lshl_add_u64 v[58:59], v[58:59], 0, v[140:141]
	v_lshlrev_b64 v[58:59], 1, v[58:59]
	v_lshl_add_u64 v[60:61], v[106:107], 0, v[58:59]
	v_lshl_add_u64 v[58:59], v[108:109], 0, v[58:59]
	global_load_dwordx4 v[78:81], v[60:61], off
	global_load_dwordx4 v[86:89], v[58:59], off
	v_add_u32_e32 v58, s36, v161
	v_ashrrev_i32_e32 v59, 31, v58
	v_lshlrev_b64 v[58:59], 11, v[58:59]
	v_lshl_add_u64 v[58:59], v[58:59], 0, v[142:143]
	v_lshlrev_b64 v[58:59], 1, v[58:59]
	v_lshl_add_u64 v[60:61], v[106:107], 0, v[58:59]
	v_lshl_add_u64 v[58:59], v[108:109], 0, v[58:59]
	global_load_dwordx4 v[90:93], v[60:61], off
	global_load_dwordx4 v[94:97], v[58:59], off
	v_add_u32_e32 v58, s36, v163
	v_ashrrev_i32_e32 v59, 31, v58
	v_lshlrev_b64 v[58:59], 11, v[58:59]
	v_lshl_add_u64 v[58:59], v[58:59], 0, v[144:145]
	v_lshlrev_b64 v[58:59], 1, v[58:59]
	v_lshl_add_u64 v[60:61], v[106:107], 0, v[58:59]
	v_lshl_add_u64 v[58:59], v[108:109], 0, v[58:59]
	global_load_dwordx4 v[98:101], v[60:61], off
	global_load_dwordx4 v[102:105], v[58:59], off
	v_or_b32_e32 v58, s36, v113
	v_ashrrev_i32_e32 v59, 31, v58
	v_lshlrev_b64 v[58:59], 12, v[58:59]
	v_lshl_add_u64 v[58:59], v[146:147], 0, v[58:59]
	global_load_dwordx4 v[58:61], v[58:59], off
	s_or_b64 s[28:29], s[4:5], s[28:29]
	s_and_b64 vcc, exec, s[28:29]
	s_cbranch_vccz .LBB0_805
	v_add_u32_e32 v34, v152, v117
	v_add_u32_e32 v178, v153, v117
	ds_read_b128 v[6:9], v34
	ds_read_b128 v[10:13], v34 offset:64
	ds_read_b128 v[14:17], v34 offset:128
	ds_read_b128 v[18:21], v34 offset:192
	ds_read_b128 v[22:25], v34 offset:256
	ds_read_b128 v[26:29], v34 offset:320
	ds_read_b128 v[30:33], v34 offset:384
	ds_read_b128 v[34:37], v34 offset:448
	ds_read_b128 v[192:195], v178 offset:34816
	ds_read_b128 v[196:199], v178 offset:34880
	ds_read_b128 v[200:203], v178 offset:43520
	ds_read_b128 v[204:207], v178 offset:43584
	ds_read_b128 v[208:211], v178 offset:34944
	ds_read_b128 v[212:215], v178 offset:35008
	ds_read_b128 v[216:219], v178 offset:43648
	ds_read_b128 v[228:231], v178 offset:43712
	s_waitcnt lgkmcnt(7)
	v_mfma_f32_16x16x32_bf16 v[192:195], v[192:195], v[6:9], v[2:5]
	s_waitcnt lgkmcnt(5)
	v_mfma_f32_16x16x32_bf16 v[200:203], v[200:203], v[6:9], v[2:5]
	v_mfma_f32_16x16x32_bf16 v[192:195], v[196:199], v[10:13], v[192:195]
	s_waitcnt lgkmcnt(4)
	v_mfma_f32_16x16x32_bf16 v[196:199], v[204:207], v[10:13], v[200:203]
	s_waitcnt lgkmcnt(3)
	v_mfma_f32_16x16x32_bf16 v[192:195], v[208:211], v[14:17], v[192:195]
	s_waitcnt lgkmcnt(1)
	v_mfma_f32_16x16x32_bf16 v[196:199], v[216:219], v[14:17], v[196:199]
	v_mfma_f32_16x16x32_bf16 v[192:195], v[212:215], v[18:21], v[192:195]
	s_waitcnt lgkmcnt(0)
	v_mfma_f32_16x16x32_bf16 v[196:199], v[228:231], v[18:21], v[196:199]
	ds_read_b128 v[200:203], v178 offset:35072
	ds_read_b128 v[204:207], v178 offset:35136
	ds_read_b128 v[208:211], v178 offset:43776
	ds_read_b128 v[212:215], v178 offset:43840
	ds_read_b128 v[216:219], v178 offset:35200
	ds_read_b128 v[228:231], v178 offset:35264
	ds_read_b128 v[232:235], v178 offset:43904
	ds_read_b128 v[236:239], v178 offset:43968
	s_waitcnt lgkmcnt(7)
	v_mfma_f32_16x16x32_bf16 v[192:195], v[200:203], v[22:25], v[192:195]
	s_waitcnt lgkmcnt(5)
	v_mfma_f32_16x16x32_bf16 v[196:199], v[208:211], v[22:25], v[196:199]
	v_mfma_f32_16x16x32_bf16 v[192:195], v[204:207], v[26:29], v[192:195]
	s_waitcnt lgkmcnt(4)
	v_mfma_f32_16x16x32_bf16 v[196:199], v[212:215], v[26:29], v[196:199]
	s_waitcnt lgkmcnt(3)
	v_mfma_f32_16x16x32_bf16 v[192:195], v[216:219], v[30:33], v[192:195]
	s_waitcnt lgkmcnt(1)
	v_mfma_f32_16x16x32_bf16 v[196:199], v[232:235], v[30:33], v[196:199]
	v_mfma_f32_16x16x32_bf16 v[192:195], v[228:231], v[34:37], v[192:195]
	s_waitcnt lgkmcnt(0)
	v_mfma_f32_16x16x32_bf16 v[196:199], v[236:239], v[34:37], v[196:199]
	s_nop 5
	v_cndmask_b32_e64 v178, v192, 0, s[8:9]
	v_cndmask_b32_e64 v179, 0, v193, s[10:11]
	v_cvt_pk_bf16_f32 v178, v178, v179
	v_cndmask_b32_e64 v179, v194, 0, s[12:13]
	v_cndmask_b32_e64 v180, v195, 0, s[14:15]
	v_cvt_pk_bf16_f32 v179, v179, v180
	v_add_u32_e32 v180, v158, v148
	ds_write_b64 v180, v[178:179]
	v_cndmask_b32_e64 v178, v196, 0, s[16:17]
	v_cndmask_b32_e64 v179, v197, 0, s[18:19]
	v_cvt_pk_bf16_f32 v178, v178, v179
	v_cndmask_b32_e64 v179, v198, 0, s[20:21]
	v_cndmask_b32_e64 v180, v199, 0, s[22:23]
	v_cvt_pk_bf16_f32 v179, v179, v180
	v_add_u32_e32 v180, v159, v148
	ds_write_b64 v180, v[178:179]
;     ...
;             {
;                 mx_bf16x8 vt[4][2], ak[DT][2]; f32x4 dec[DT];
; #pragma unroll
;                 for (int te = 0; te < 4; ++te) { vt[te][0] = frag_row8(L + O_VT, 16 * te, 0, lane); vt[te][1] = frag_row8(L + O_VT, 16 * te, 32, lane); }
; #pragma unroll
;                 for (int td = 0; td < DT; ++td) { const int d0 = 16 * (DT * w + td);
;                     ak[td][0] = frag_tr(L + (HG ? 3 : 1) * IMG, QS, 0, d0, lane); ak[td][1] = frag_tr(L + (HG ? 3 : 1) * IMG, QS, 32, d0, lane);
;                     dec[td] = (f32x4){cdec, cdec, cdec, cdec};
;                     if (HG) { const f32x4 ce = *(const LAS f32x4*)(L + O_TOT + 2048 + (d0 + 4 * g) * 4); dec[td] = (f32x4){__expf(ce[0]), __expf(ce[1]), __expf(ce[2]), __expf(ce[3])}; } }
;                 __builtin_amdgcn_sched_barrier(0);
; #pragma unroll
;                 for (int td = 0; td < DT; ++td)
; #pragma unroll
;                     for (int te = 0; te < 4; ++te) accS[td][te] = MX_MFMA(ak[td][0], vt[te][0], accS[td][te] * dec[td]);
; #pragma unroll
;                 for (int td = 0; td < DT; ++td)
; #pragma unroll
;                     for (int te = 0; te < 4; ++te) accS[td][te] = MX_MFMA(ak[td][1], vt[te][1], accS[td][te]);
;             }
;             MX_BAR();
;             if (do_out) {
;                 if (HG) {
; #pragma unroll
;                     for (int ks = 0; ks < KS; ++ks) aq[ks] = frag_row(L + 2 * IMG, QS, nq0, 32 * ks, lane);
;                 }
;                 mx_bf16x8 vo[2][2];
;                 const mx_bf16x8 bp0 = frag_row8(L + O_P, nq0, 0, lane), bp1 = frag_row8(L + O_P, nq0, 32, lane);
; #pragma unroll
;                 for (int te = 0; te < 2; ++te) { vo[te][0] = frag_row8(L + O_VT, 32 * cg + 16 * te, 0, lane); vo[te][1] = frag_row8(L + O_VT, 32 * cg + 16 * te, 32, lane); }
;                 const int grow = rlo + (dir ? 63 - (nq0 + i) : (nq0 + i));
;                 for (int rep2 = 0; rep2 < MXP_S2; ++rep2) {
;                 f32x4 o1a = ZERO4, o1b = o1a, o2a = o1a, o2b = o1a;
; #pragma unroll
;                 for (int kb = 0; kb < KS; kb += 4) {
;                     mx_bf16x8 st[2][4];
; #pragma unroll
;                     for (int ks = 0; ks < 4; ++ks) { st[0][ks] = frag_row(L + O_ST, QS, 32 * cg, 32 * (kb + ks), lane); st[1][ks] = frag_row(L + O_ST, QS, 32 * cg + 16, 32 * (kb + ks), lane); }
;                     __builtin_amdgcn_sched_barrier(0);
.LBB0_805:
	v_add_u32_e32 v192, v167, v117
	ds_read_b128 v[194:197], v192
	ds_read_b128 v[198:201], v192 offset:64
	ds_read_b128 v[202:205], v171
	ds_read_b128 v[206:209], v171 offset:64
	ds_read_b128 v[210:213], v172
	ds_read_b128 v[214:217], v172 offset:64
	ds_read_b128 v[228:231], v173
	ds_read_b128 v[232:235], v173 offset:64
	ds_read_b64_tr_b16 v[236:237], v174 offset:34816
	ds_read_b64_tr_b16 v[238:239], v174 offset:36992
	ds_read_b64_tr_b16 v[242:243], v174 offset:37024
	ds_read_b64_tr_b16 v[240:241], v174 offset:34848
	ds_read_b64_tr_b16 v[244:245], v174 offset:52224
	ds_read_b64_tr_b16 v[246:247], v174 offset:54400
	ds_read_b64_tr_b16 v[250:251], v174 offset:54432
	ds_read_b64_tr_b16 v[248:249], v174 offset:52256
	v_pk_mul_f32 v[84:85], v[134:135], v[84:85]
	v_pk_mul_f32 v[82:83], v[130:131], v[82:83]
	v_pk_mul_f32 v[72:73], v[134:135], v[72:73]
	v_pk_mul_f32 v[70:71], v[130:131], v[70:71]
	v_pk_mul_f32 v[64:65], v[134:135], v[64:65]
	v_pk_mul_f32 v[62:63], v[130:131], v[62:63]
	v_pk_mul_f32 v[56:57], v[134:135], v[56:57]
	v_pk_mul_f32 v[54:55], v[130:131], v[54:55]
	v_pk_mul_f32 v[52:53], v[134:135], v[52:53]
	v_pk_mul_f32 v[50:51], v[130:131], v[50:51]
	v_pk_mul_f32 v[48:49], v[134:135], v[48:49]
	v_pk_mul_f32 v[46:47], v[130:131], v[46:47]
	v_pk_mul_f32 v[44:45], v[134:135], v[44:45]
	v_pk_mul_f32 v[42:43], v[130:131], v[42:43]
	v_pk_mul_f32 v[40:41], v[134:135], v[40:41]
	v_pk_mul_f32 v[38:39], v[130:131], v[38:39]
	s_waitcnt lgkmcnt(6)
	v_mfma_f32_16x16x32_bf16 v[82:85], v[236:239], v[194:197], v[82:85]
	s_waitcnt lgkmcnt(0)
	s_barrier
	v_mfma_f32_16x16x32_bf16 v[70:73], v[236:239], v[202:205], v[70:73]
	s_andn2_b64 vcc, exec, s[28:29]
	v_mfma_f32_16x16x32_bf16 v[62:65], v[236:239], v[210:213], v[62:65]
	v_mfma_f32_16x16x32_bf16 v[54:57], v[236:239], v[228:231], v[54:57]
	s_waitcnt lgkmcnt(4)
	v_mfma_f32_16x16x32_bf16 v[50:53], v[240:243], v[194:197], v[50:53]
	v_mfma_f32_16x16x32_bf16 v[46:49], v[240:243], v[202:205], v[46:49]
	v_mfma_f32_16x16x32_bf16 v[42:45], v[240:243], v[210:213], v[42:45]
	v_mfma_f32_16x16x32_bf16 v[38:41], v[240:243], v[228:231], v[38:41]
	s_waitcnt lgkmcnt(2)
	v_mfma_f32_16x16x32_bf16 v[82:85], v[244:247], v[198:201], v[82:85]
	v_mfma_f32_16x16x32_bf16 v[70:73], v[244:247], v[206:209], v[70:73]
	v_mfma_f32_16x16x32_bf16 v[62:65], v[244:247], v[214:217], v[62:65]
	v_mfma_f32_16x16x32_bf16 v[54:57], v[244:247], v[232:235], v[54:57]
	s_waitcnt lgkmcnt(0)
	v_mfma_f32_16x16x32_bf16 v[50:53], v[248:251], v[198:201], v[50:53]
	v_mfma_f32_16x16x32_bf16 v[46:49], v[248:251], v[206:209], v[46:49]
	v_mfma_f32_16x16x32_bf16 v[42:45], v[248:251], v[214:217], v[42:45]
	v_mfma_f32_16x16x32_bf16 v[38:41], v[248:251], v[232:235], v[38:41]
	s_cbranch_vccnz .LBB0_807
	v_sub_co_u32_e64 v178, s[28:29], s27, 4
	s_and_b64 s[36:37], s[24:25], exec
	v_readfirstlane_b32 s36, v178
	s_cselect_b32 s36, s36, s35
	s_lshl_b32 s40, s36, 6
	s_sub_i32 s35, s35, 64
	s_and_b64 s[36:37], s[24:25], exec
	s_cselect_b32 s27, s27, s35
	s_lshl_b32 s27, s27, 6
	s_add_i32 s27, s27, s26
	s_add_i32 s40, s40, s30
	s_and_b64 s[28:29], s[28:29], exec
	v_add_u32_e32 v178, v154, v117
	s_cselect_b32 s27, s27, s40
	ds_read_b128 v[194:197], v178
	ds_read_b128 v[198:201], v178 offset:64
	v_add_u32_e32 v178, v168, v117
	ds_read_b128 v[202:205], v178
	ds_read_b128 v[206:209], v178 offset:64
	ds_read_b128 v[210:213], v178 offset:2560
	ds_read_b128 v[214:217], v178 offset:2624
	v_add_u32_e32 v178, s27, v176
	v_ashrrev_i32_e32 v179, 31, v178
	v_lshlrev_b64 v[178:179], 12, v[178:179]
	v_add_u32_e32 v193, v155, v117
	v_lshl_add_u64 v[218:219], v[132:133], 0, v[178:179]
	ds_read_b128 v[228:231], v193
	ds_read_b128 v[232:235], v193 offset:8704
	ds_read_b128 v[236:239], v193 offset:64
	ds_read_b128 v[240:243], v193 offset:8768
	ds_read_b128 v[244:247], v193 offset:128
	ds_read_b128 v[248:251], v193 offset:8832
	ds_read_b128 v[178:181], v193 offset:192
	ds_read_b128 v[224:227], v193 offset:8896
	s_waitcnt lgkmcnt(11)
	v_mfma_f32_16x16x32_bf16 v[202:205], v[202:205], v[194:197], v[2:5]
	s_waitcnt lgkmcnt(9)
	v_mfma_f32_16x16x32_bf16 v[194:197], v[210:213], v[194:197], v[2:5]
	v_mfma_f32_16x16x32_bf16 v[202:205], v[206:209], v[198:201], v[202:205]
	s_waitcnt lgkmcnt(8)
	v_mfma_f32_16x16x32_bf16 v[194:197], v[214:217], v[198:201], v[194:197]
	s_waitcnt lgkmcnt(7)
	v_mfma_f32_16x16x32_bf16 v[198:201], v[228:231], v[6:9], v[2:5]
	s_waitcnt lgkmcnt(6)
	v_mfma_f32_16x16x32_bf16 v[206:209], v[232:235], v[6:9], v[2:5]
	s_waitcnt lgkmcnt(5)
	v_mfma_f32_16x16x32_bf16 v[198:201], v[236:239], v[10:13], v[198:201]
	s_waitcnt lgkmcnt(4)
	v_mfma_f32_16x16x32_bf16 v[206:209], v[240:243], v[10:13], v[206:209]
	s_waitcnt lgkmcnt(3)
	v_mfma_f32_16x16x32_bf16 v[198:201], v[244:247], v[14:17], v[198:201]
	s_waitcnt lgkmcnt(2)
	v_mfma_f32_16x16x32_bf16 v[206:209], v[248:251], v[14:17], v[206:209]
	s_waitcnt lgkmcnt(1)
	v_mfma_f32_16x16x32_bf16 v[178:181], v[178:181], v[18:21], v[198:201]
	s_waitcnt lgkmcnt(0)
	v_mfma_f32_16x16x32_bf16 v[198:201], v[224:227], v[18:21], v[206:209]
	s_nop 3
	ds_read_b128 v[206:209], v193 offset:256
	ds_read_b128 v[210:213], v193 offset:320
	ds_read_b128 v[214:217], v193 offset:8960
	ds_read_b128 v[224:227], v193 offset:9024
	ds_read_b128 v[228:231], v193 offset:384
	ds_read_b128 v[232:235], v193 offset:448
	ds_read_b128 v[236:239], v193 offset:9088
	ds_read_b128 v[240:243], v193 offset:9152
	s_waitcnt lgkmcnt(7)
	v_mfma_f32_16x16x32_bf16 v[178:181], v[206:209], v[22:25], v[178:181]
	s_waitcnt lgkmcnt(5)
	v_mfma_f32_16x16x32_bf16 v[198:201], v[214:217], v[22:25], v[198:201]
	v_mfma_f32_16x16x32_bf16 v[178:181], v[210:213], v[26:29], v[178:181]
	s_waitcnt lgkmcnt(4)
	v_mfma_f32_16x16x32_bf16 v[198:201], v[224:227], v[26:29], v[198:201]
	s_waitcnt lgkmcnt(3)
	v_mfma_f32_16x16x32_bf16 v[178:181], v[228:231], v[30:33], v[178:181]
	s_waitcnt lgkmcnt(1)
	v_mfma_f32_16x16x32_bf16 v[198:201], v[236:239], v[30:33], v[198:201]
	v_mfma_f32_16x16x32_bf16 v[178:181], v[232:235], v[34:37], v[178:181]
	s_waitcnt lgkmcnt(0)
	v_mfma_f32_16x16x32_bf16 v[198:201], v[240:243], v[34:37], v[198:201]
	s_nop 5
	v_mul_f32_e64 v180, v128, v180
	v_mul_f32_e64 v181, v129, v181
	v_pk_mul_f32 v[178:179], v[124:125], v[178:179]
	v_pk_fma_f32 v[180:181], v[126:127], v[204:205], v[180:181]
	v_pk_fma_f32 v[178:179], v[122:123], v[202:203], v[178:179]
	v_pk_mul_f32 v[200:201], v[128:129], v[200:201]
	v_pk_mul_f32 v[198:199], v[124:125], v[198:199]
	v_pk_fma_f32 v[196:197], v[126:127], v[196:197], v[200:201]
	v_pk_fma_f32 v[194:195], v[122:123], v[194:195], v[198:199]
	v_cvt_pk_bf16_f32 v178, v178, v179
	v_cvt_pk_bf16_f32 v179, v180, v181
	v_cvt_pk_bf16_f32 v180, v194, v195
	v_cvt_pk_bf16_f32 v181, v196, v197
	global_store_dwordx2 v[218:219], v[178:179], off
	global_store_dwordx2 v[218:219], v[180:181], off offset:32
; #define LAS __attribute__((address_space(3)))
; __device__ __forceinline__ unsigned pk2(float lo, float hi) { const f32x2_t v = {lo, hi}; const bf16x2_t b = __builtin_convertvector(v, bf16x2_t); return __builtin_bit_cast(unsigned, b); }
; #define MX_BAR() do { asm volatile("s_waitcnt lgkmcnt(0)" ::: "memory"); __builtin_amdgcn_s_barrier(); if (MXP_BAR > 1) __builtin_amdgcn_s_barrier(); asm volatile("" ::: "memory"); } while (0)
;     ...
;             MX_BAR();
; #pragma unroll
;             for (int td = 0; td < DT; ++td)
; #pragma unroll
;                 for (int te = 0; te < 4; ++te) { const int d0 = 16 * (DT * w + td); const f32x4 s = accS[td][te];
;                     v2u sw; sw.x = pk2(s[0], s[1]); sw.y = pk2(s[2], s[3]);
;                     *(LAS v2u*)(L + O_ST + (16 * te + i) * QS + 16 * (((d0 + 4 * g) >> 3) ^ sw16(16 * te + i)) + ((d0 + 4 * g) & 7) * 2) = sw; }
.LBB0_807:
	v_cvt_pk_bf16_f32 v178, v82, v83
	v_cvt_pk_bf16_f32 v179, v84, v85
	s_nop 1
	v_cvt_pk_bf16_f32 v194, v50, v51
	v_cvt_pk_bf16_f32 v195, v52, v53
	s_waitcnt lgkmcnt(0)
	s_barrier
	v_cvt_pk_bf16_f32 v180, v70, v71
	v_cvt_pk_bf16_f32 v181, v72, v73
	ds_write2_b64 v175, v[178:179], v[194:195] offset1:4
	v_cvt_pk_bf16_f32 v178, v46, v47
	v_cvt_pk_bf16_f32 v179, v48, v49
	v_add_u32_e32 v193, 0x2000, v175
	v_cvt_pk_bf16_f32 v196, v62, v63
	v_cvt_pk_bf16_f32 v197, v64, v65
	ds_write2_b64 v193, v[180:181], v[178:179] offset0:64 offset1:68
	v_cvt_pk_bf16_f32 v178, v42, v43
	v_cvt_pk_bf16_f32 v179, v44, v45
	v_add_u32_e32 v194, 0x4000, v175
	v_cvt_pk_bf16_f32 v198, v54, v55
	v_cvt_pk_bf16_f32 v199, v56, v57
	ds_write2_b64 v194, v[196:197], v[178:179] offset0:128 offset1:132
	v_cvt_pk_bf16_f32 v178, v38, v39
	v_cvt_pk_bf16_f32 v179, v40, v41
	v_add_u32_e32 v195, 0x6000, v175
	s_cmpk_eq_i32 s31, 0x43
	ds_write2_b64 v195, v[198:199], v[178:179] offset0:192 offset1:196
	s_cbranch_scc1 .LBB0_798
	s_mov_b32 s35, s34
	s_mov_b32 s27, s31
	s_branch .LBB0_803
